# GEMM3 unit preheader: the two kernarg pointers used by the hoisted conv-weight load are loaded once at phase setup and parked in v255 lanes 20-23 (v_readlane per unit instead of s_load + lgkmcnt wait)
# baseline (speedup 1.0000x reference)
; #define PG8_STAGE(bufoff, gbase, voff) do { _Pragma("unroll") for (int _i = 0; _i < 2; ++_i) \
;         __builtin_amdgcn_global_load_lds((const unsigned*)((const char*)(gbase) + (voff)[_i]), (PG8_LAS unsigned*)(lds + (bufoff) + ldsw + _i * 8192), 16, 0, 0); } while (0)
; #define PG8_WAIT_V(n) asm volatile("s_waitcnt vmcnt(" #n ")" ::: "memory")
; #define PG8_BAR __builtin_amdgcn_s_barrier()
; #define LAS __attribute__((address_space(3)))
; template <class Epi, class Sched, bool ALIGN_EPI = false, bool SP2 = false, bool A_TILED = false, bool B_TILED = false>
; __device__ __forceinline__ void gemm_phase(PG8_LAS unsigned char* lds, const Gemm g, const Sched& S, const Epi& E) {
;     ...
;         PG8_STAGE(PG8_SB(0, 0), cB, voffB); PG8_STAGE(PG8_SA(0, 0), cA, voffA); PG8_STAGE(PG8_SB(0, 1), cB + hstepB, voffB); PG8_STAGE(PG8_SA(0, 1), cA + hstepA, voffA);
;         if (wr == 1) PG8_BAR;
;         PG8_WAIT_V(4); PG8_BAR;
;         PG8_STAGE(PG8_SB(1, 0), cB + kstepB, voffB); PG8_STAGE(PG8_SA(1, 0), cA + kstepA, voffA); PG8_STAGE(PG8_SB(1, 1), cB + hstepB + kstepB, voffB);
;         PG8_WAIT_V(6); PG8_BAR;
;     }
; __global__ void __launch_bounds__(NWAVES * 64, 2) hymba_fwd(Args args) {
;     ...
;         pg8::Gemm g{P_X1B, P_W3, M, NGU, DM};
;         pg8::EpiGateUp E{P_ACT, P_fconv_w, P_fconv_b, P_st_ffn, (float*)(P_ws + WS_FIX), P_out, (LAS float*)(F.lds + CWL_OFF), P_ssq2};
;         { pg8::Gemm3BlockOrder S{F.G, F.bid, DM / 64};
;           pg8::gemm_phase<pg8::EpiGateUp, pg8::Gemm3BlockOrder, true, PG8_SP2>(F.lds + RING_OFF, g, S, E); }
.LBB0_703:
	s_add_u32 s40, s50, 0x2cf00000
	s_addc_u32 s41, s51, 0
	s_add_u32 s42, s50, 0x2a800000
	s_addc_u32 s43, s51, 0
	s_add_u32 s44, s50, 0x24000
	s_addc_u32 s45, s51, 0
	s_lshl_b32 s4, s4, 5
	s_mov_b64 s[46:47], 0x80
	s_and_b32 s33, s4, 0x60
	s_add_i32 m0, s93, 0x18000
	v_lshl_add_u64 v[8:9], v[8:9], 0, s[46:47]
	s_lshl_b32 s97, s13, 6
	s_lshl_b32 s15, s13, 13
	s_lshl_b32 s16, s33, 7
	s_waitcnt vmcnt(2)
	s_barrier
	global_load_lds_dwordx4 v[8:9], off
	v_lshl_add_u64 v[6:7], v[6:7], 0, s[46:47]
	s_add_i32 m0, s93, 0x1a000
	s_add_i32 s54, s93, 0x8000
	s_add_i32 s55, s93, 0xa000
	global_load_lds_dwordx4 v[6:7], off
	v_lshl_add_u64 v[4:5], v[4:5], 0, s[46:47]
	s_mov_b32 m0, s54
	s_add_u32 s4, s10, 0x100080
	global_load_lds_dwordx4 v[4:5], off
	v_lshl_add_u64 v[2:3], v[2:3], 0, s[46:47]
	s_mov_b32 m0, s55
	s_addc_u32 s5, s11, 0
	global_load_lds_dwordx4 v[2:3], off
	s_add_i32 m0, s93, 0x1c000
	v_lshl_add_u64 v[2:3], s[4:5], 0, v[172:173]
	global_load_lds_dwordx4 v[2:3], off
	v_lshl_add_u64 v[2:3], s[4:5], 0, v[176:177]
	s_add_i32 m0, s93, 0x1e000
	v_bfe_u32 v202, v0, 4, 2
	global_load_lds_dwordx4 v[2:3], off
	v_lshlrev_b32_e32 v2, 4, v202
	v_lshlrev_b32_e32 v4, 2, v199
	v_lshl_or_b32 v3, v199, 6, v2
	v_and_b32_e32 v4, 32, v4
	s_cmpk_lt_u32 s12, 0x100
	v_bitop3_b32 v3, v3, s15, v4 bitop3:0xde
	v_or_b32_e32 v2, v2, v200
	s_cselect_b64 s[56:57], -1, 0
	s_lshl_b32 s15, s13, 1
	v_bitop3_b32 v203, s16, v2, v201 bitop3:0xf6
	s_add_i32 s15, s15, 0x7ffff2
	s_xor_b64 s[16:17], s[38:39], -1
	s_cmpk_gt_u32 s12, 0xff
	s_cselect_b64 s[58:59], -1, 0
	s_lshl_b32 s12, s13, 8
	v_writelane_b32 v255, s15, 2
	s_add_u32 s13, s44, s12
	v_lshlrev_b32_e32 v2, 1, v0
	v_writelane_b32 v255, s13, 7
	s_addc_u32 s13, s45, 0
	v_and_b32_e32 v204, 0x7e, v2
	v_cndmask_b32_e64 v2, 0, 1, s[16:17]
	v_writelane_b32 v255, s13, 8
	s_and_b32 s13, s2, 7
	v_or_b32_e32 v2, s14, v2
	v_writelane_b32 v255, s13, 9
	s_ashr_i32 s13, s2, 3
	s_ashr_i32 s14, s2, 4
	s_and_b32 s14, s14, -8
	s_and_b32 s15, s13, 7
	s_or_b32 s14, s14, s15
	v_writelane_b32 v255, s15, 10
	s_addk_i32 s14, 0xfa20
	v_writelane_b32 v255, s14, 11
	s_bfe_u32 s14, s2, 0x10006
	s_or_b32 s14, s14, 0x54
	s_and_b32 s13, s13, 3
	v_writelane_b32 v255, s14, 12
	s_or_b32 s13, s13, 32
	v_writelane_b32 v255, s13, 13
	s_ashr_i32 s13, s2, 5
	v_lshlrev_b32_e32 v2, 10, v2
	s_addk_i32 s13, 0xfd60
	s_add_i32 s61, 0, 0x22000
	v_writelane_b32 v255, s13, 14
	s_ashr_i32 s13, s2, 6
	v_add_u32_e32 v206, s61, v2
	v_lshlrev_b32_e32 v2, 10, v0
	s_waitcnt lgkmcnt(0)
	s_add_u32 s14, s34, 0x9630000
	v_and_b32_e32 v2, 0x60000, v2
	v_lshlrev_b32_e32 v4, 13, v196
	s_addc_u32 s15, s35, 0
	s_add_i32 s29, s12, 0
	v_or3_b32 v2, v1, v2, v4
	v_writelane_b32 v255, s13, 15
	s_add_i32 s28, s29, 0x23000
	v_add_u32_e32 v180, v2, v195
	v_lshlrev_b32_e32 v2, 6, v197
	s_waitcnt vmcnt(6)
	v_writelane_b32 v255, s14, 16
	s_add_u32 s62, s34, 0x15c86000
	v_and_b32_e32 v2, 0xe0000, v2
	s_movk_i32 s4, 0xff
	v_writelane_b32 v255, s15, 17
	s_addc_u32 s63, s35, 0
	v_or3_b32 v2, v1, v2, v4
	s_add_i32 s24, 0, 0x10000
	s_add_i32 s25, 0, 0x14000
	s_add_i32 s12, 0, 0x22800
	v_cmp_lt_u32_e64 s[4:5], s4, v0
	v_lshl_add_u32 v205, v0, 2, s61
	s_add_i32 s29, s29, 0x23200
	v_mov_b32_e32 v181, v179
	v_add_u32_e32 v182, v2, v195
	v_mov_b32_e32 v183, v179
	v_add_u32_e32 v207, s24, v203
	v_add_u32_e32 v208, s25, v203
	v_add_u32_e32 v209, 0, v3
	s_mov_b32 s26, 0xac00
	v_mov_b32_e32 v210, 0x358637bd
	s_mov_b32 s27, 0xf800000
	v_mov_b32_e32 v211, 0x260
	v_writelane_b32 v255, s12, 18
	s_mov_b32 s53, 0x15800
	s_movk_i32 s60, 0xac
	s_barrier
	s_load_dwordx2 s[98:99], s[0:1], 0xb8
	s_load_dwordx2 s[100:101], s[0:1], 0xc0
	s_waitcnt lgkmcnt(0)
	v_writelane_b32 v255, s98, 20
	v_writelane_b32 v255, s99, 21
	v_writelane_b32 v255, s100, 22
	v_writelane_b32 v255, s101, 23
	s_branch .LBB0_706

; #define PG8_LAS __attribute__((address_space(3)))
;     __device__ __forceinline__ void operator()(const f32x4 (&acc)[2][2][4][2], const Unit& u, int wr, int wc, int fr, int fq) const {
;     ...
;         PG8_LAS float* const T = E - 2048;
;         { const int tid_ = threadIdx.x; if (tid_ < 256) E[1024 + tid_] = 1.0f / sqrtf(ssq[u.pm * BM + tid_] * (1.0f / DM) + EPS);
;           else { const int wv_ = __builtin_amdgcn_readfirstlane(tid_ >> 6) - 4; int l2_ = 2 * (tid_ & 63); asm volatile("" : "+v"(l2_));
;                  const float* src_ = ((wv_ == 3) ? cb : cw + (size_t)wv_ * DFF) + u.pn * 128; typedef float f32x2e __attribute__((ext_vector_type(2)));
;                  *(PG8_LAS f32x2e*)(T + wv_ * 128 + l2_) = *(const f32x2e*)(src_ + l2_); } }
.Lg3h_w47:
	v_readlane_b32 s98, v255, 20
	v_readlane_b32 s99, v255, 21
	v_readlane_b32 s100, v255, 22
	v_readlane_b32 s101, v255, 23
	v_readfirstlane_b32 vcc_lo, v0
	s_lshr_b32 vcc_lo, vcc_lo, 6
	s_add_i32 vcc_lo, vcc_lo, -4
	s_nop 0
	s_cmp_eq_u32 vcc_lo, 3
	s_cbranch_scc1 .Lg3h_w7
	s_mul_i32 vcc_lo, vcc_lo, 0xac00
	s_add_u32 s100, s98, vcc_lo
	s_addc_u32 s101, s99, 0
